# attention output: 4x4 register transpose (v_perm + quad DPP) so each lane stores 16 dwordx2 instead of 64 shorts
# baseline (speedup 1.0000x reference)
.LBB0_582:
	s_or_b64 exec, exec, s[6:7]
	s_waitcnt lgkmcnt(0)
	v_lshl_add_u32 v66, v175, 4, s28
	ds_read_b128 v[68:71], v66
	s_lshl_b64 s[0:1], s[4:5], 11
	s_add_u32 s0, s66, s0
	s_addc_u32 s1, s67, s1
	s_lshl_b32 s4, s16, 1
	s_add_u32 s0, s0, s4
	s_addc_u32 s1, s1, 0
	v_and_b32_e32 v144, 1, v148
	v_cmp_ne_u32_e32 vcc, 0, v144
	v_mov_b32_e32 v67, 0x01000504
	v_mov_b32_e32 v144, 0x07060302
	v_cndmask_b32_e32 v67, v67, v144, vcc
	v_and_b32_e32 v144, 3, v148
	v_lshlrev_b32_e32 v144, 11, v144
	v_lshl_or_b32 v72, v175, 13, v144
	v_lshrrev_b32_e32 v144, 2, v148
	v_lshl_or_b32 v72, v144, 3, v72
	v_and_b32_e32 v144, 2, v148
	v_cmp_ne_u32_e32 vcc, 0, v144
	s_waitcnt lgkmcnt(0)
	v_rcp_f32_e32 v68, v68
	v_rcp_f32_e32 v69, v69
	v_rcp_f32_e32 v70, v70
	v_rcp_f32_e32 v71, v71
	s_nop 0
	v_pk_mul_f32 v[0:1], v[0:1], v[68:69]
	v_pk_mul_f32 v[2:3], v[2:3], v[70:71]
	v_cvt_pk_bf16_f32 v0, v0, v1
	v_cvt_pk_bf16_f32 v2, v2, v3
	s_nop 1
	v_mov_b32_dpp v64, v0 quad_perm:[1,0,3,2] row_mask:0xf bank_mask:0xf
	v_mov_b32_dpp v65, v2 quad_perm:[1,0,3,2] row_mask:0xf bank_mask:0xf
	v_perm_b32 v0, v0, v64, v67
	v_perm_b32 v2, v2, v65, v67
	v_cndmask_b32_e32 v73, v2, v0, vcc
	s_nop 1
	v_mov_b32_dpp v64, v73 quad_perm:[2,3,0,1] row_mask:0xf bank_mask:0xf
	v_cndmask_b32_e32 v1, v64, v2, vcc
	v_cndmask_b32_e32 v0, v0, v64, vcc
	global_store_dwordx2 v72, v[0:1], s[0:1]
	v_pk_mul_f32 v[48:49], v[48:49], v[68:69]
	v_pk_mul_f32 v[50:51], v[50:51], v[70:71]
	v_cvt_pk_bf16_f32 v48, v48, v49
	v_cvt_pk_bf16_f32 v50, v50, v51
	s_nop 1
	v_mov_b32_dpp v64, v48 quad_perm:[1,0,3,2] row_mask:0xf bank_mask:0xf
	v_mov_b32_dpp v65, v50 quad_perm:[1,0,3,2] row_mask:0xf bank_mask:0xf
	v_perm_b32 v48, v48, v64, v67
	v_perm_b32 v50, v50, v65, v67
	v_cndmask_b32_e32 v73, v50, v48, vcc
	s_nop 1
	v_mov_b32_dpp v64, v73 quad_perm:[2,3,0,1] row_mask:0xf bank_mask:0xf
	v_cndmask_b32_e32 v49, v64, v50, vcc
	v_cndmask_b32_e32 v48, v48, v64, vcc
	global_store_dwordx2 v72, v[48:49], s[0:1] offset:64
	v_pk_mul_f32 v[32:33], v[32:33], v[68:69]
	v_pk_mul_f32 v[34:35], v[34:35], v[70:71]
	v_cvt_pk_bf16_f32 v32, v32, v33
	v_cvt_pk_bf16_f32 v34, v34, v35
	s_nop 1
	v_mov_b32_dpp v64, v32 quad_perm:[1,0,3,2] row_mask:0xf bank_mask:0xf
	v_mov_b32_dpp v65, v34 quad_perm:[1,0,3,2] row_mask:0xf bank_mask:0xf
	v_perm_b32 v32, v32, v64, v67
	v_perm_b32 v34, v34, v65, v67
	v_cndmask_b32_e32 v73, v34, v32, vcc
	s_nop 1
	v_mov_b32_dpp v64, v73 quad_perm:[2,3,0,1] row_mask:0xf bank_mask:0xf
	v_cndmask_b32_e32 v33, v64, v34, vcc
	v_cndmask_b32_e32 v32, v32, v64, vcc
	global_store_dwordx2 v72, v[32:33], s[0:1] offset:128
	v_pk_mul_f32 v[16:17], v[16:17], v[68:69]
	v_pk_mul_f32 v[18:19], v[18:19], v[70:71]
	v_cvt_pk_bf16_f32 v16, v16, v17
	v_cvt_pk_bf16_f32 v18, v18, v19
	s_nop 1
	v_mov_b32_dpp v64, v16 quad_perm:[1,0,3,2] row_mask:0xf bank_mask:0xf
	v_mov_b32_dpp v65, v18 quad_perm:[1,0,3,2] row_mask:0xf bank_mask:0xf
	v_perm_b32 v16, v16, v64, v67
	v_perm_b32 v18, v18, v65, v67
	v_cndmask_b32_e32 v73, v18, v16, vcc
	s_nop 1
	v_mov_b32_dpp v64, v73 quad_perm:[2,3,0,1] row_mask:0xf bank_mask:0xf
	v_cndmask_b32_e32 v17, v64, v18, vcc
	v_cndmask_b32_e32 v16, v16, v64, vcc
	global_store_dwordx2 v72, v[16:17], s[0:1] offset:192
	v_add_u32_e32 v72, 0x4000, v72
	ds_read_b64 v[2:3], v66 offset:32
	ds_read_b64 v[50:51], v66 offset:40
	ds_read_b64 v[34:35], v66 offset:64
	ds_read_b64 v[18:19], v66 offset:72
	s_waitcnt lgkmcnt(0)
	v_rcp_f32_e32 v2, v2
	v_rcp_f32_e32 v3, v3
	v_rcp_f32_e32 v50, v50
	v_rcp_f32_e32 v51, v51
	s_nop 0
	v_pk_mul_f32 v[4:5], v[4:5], v[2:3]
	v_pk_mul_f32 v[6:7], v[6:7], v[50:51]
	v_cvt_pk_bf16_f32 v4, v4, v5
	v_cvt_pk_bf16_f32 v6, v6, v7
	s_nop 1
	v_mov_b32_dpp v64, v4 quad_perm:[1,0,3,2] row_mask:0xf bank_mask:0xf
	v_mov_b32_dpp v65, v6 quad_perm:[1,0,3,2] row_mask:0xf bank_mask:0xf
	v_perm_b32 v4, v4, v64, v67
	v_perm_b32 v6, v6, v65, v67
	v_cndmask_b32_e32 v73, v6, v4, vcc
	s_nop 1
	v_mov_b32_dpp v64, v73 quad_perm:[2,3,0,1] row_mask:0xf bank_mask:0xf
	v_cndmask_b32_e32 v5, v64, v6, vcc
	v_cndmask_b32_e32 v4, v4, v64, vcc
	global_store_dwordx2 v72, v[4:5], s[0:1]
	v_pk_mul_f32 v[52:53], v[52:53], v[2:3]
	v_pk_mul_f32 v[54:55], v[54:55], v[50:51]
	v_cvt_pk_bf16_f32 v52, v52, v53
	v_cvt_pk_bf16_f32 v54, v54, v55
	s_nop 1
	v_mov_b32_dpp v64, v52 quad_perm:[1,0,3,2] row_mask:0xf bank_mask:0xf
	v_mov_b32_dpp v65, v54 quad_perm:[1,0,3,2] row_mask:0xf bank_mask:0xf
	v_perm_b32 v52, v52, v64, v67
	v_perm_b32 v54, v54, v65, v67
	v_cndmask_b32_e32 v73, v54, v52, vcc
	s_nop 1
	v_mov_b32_dpp v64, v73 quad_perm:[2,3,0,1] row_mask:0xf bank_mask:0xf
	v_cndmask_b32_e32 v53, v64, v54, vcc
	v_cndmask_b32_e32 v52, v52, v64, vcc
	global_store_dwordx2 v72, v[52:53], s[0:1] offset:64
	v_pk_mul_f32 v[36:37], v[36:37], v[2:3]
	v_pk_mul_f32 v[38:39], v[38:39], v[50:51]
	v_cvt_pk_bf16_f32 v36, v36, v37
	v_cvt_pk_bf16_f32 v38, v38, v39
	s_nop 1
	v_mov_b32_dpp v64, v36 quad_perm:[1,0,3,2] row_mask:0xf bank_mask:0xf
	v_mov_b32_dpp v65, v38 quad_perm:[1,0,3,2] row_mask:0xf bank_mask:0xf
	v_perm_b32 v36, v36, v64, v67
	v_perm_b32 v38, v38, v65, v67
	v_cndmask_b32_e32 v73, v38, v36, vcc
	s_nop 1
	v_mov_b32_dpp v64, v73 quad_perm:[2,3,0,1] row_mask:0xf bank_mask:0xf
	v_cndmask_b32_e32 v37, v64, v38, vcc
	v_cndmask_b32_e32 v36, v36, v64, vcc
	global_store_dwordx2 v72, v[36:37], s[0:1] offset:128
	v_pk_mul_f32 v[20:21], v[20:21], v[2:3]
	v_pk_mul_f32 v[22:23], v[22:23], v[50:51]
	v_cvt_pk_bf16_f32 v20, v20, v21
	v_cvt_pk_bf16_f32 v22, v22, v23
	s_nop 1
	v_mov_b32_dpp v64, v20 quad_perm:[1,0,3,2] row_mask:0xf bank_mask:0xf
	v_mov_b32_dpp v65, v22 quad_perm:[1,0,3,2] row_mask:0xf bank_mask:0xf
	v_perm_b32 v20, v20, v64, v67
	v_perm_b32 v22, v22, v65, v67
	v_cndmask_b32_e32 v73, v22, v20, vcc
	s_nop 1
	v_mov_b32_dpp v64, v73 quad_perm:[2,3,0,1] row_mask:0xf bank_mask:0xf
	v_cndmask_b32_e32 v21, v64, v22, vcc
	v_cndmask_b32_e32 v20, v20, v64, vcc
	global_store_dwordx2 v72, v[20:21], s[0:1] offset:192
	v_add_u32_e32 v72, 0x4000, v72
	ds_read_b64 v[6:7], v66 offset:96
	ds_read_b64 v[54:55], v66 offset:104
	v_rcp_f32_e32 v34, v34
	v_rcp_f32_e32 v35, v35
	v_rcp_f32_e32 v18, v18
	v_rcp_f32_e32 v19, v19
	s_nop 0
	v_pk_mul_f32 v[8:9], v[8:9], v[34:35]
	v_pk_mul_f32 v[10:11], v[10:11], v[18:19]
	v_cvt_pk_bf16_f32 v8, v8, v9
	v_cvt_pk_bf16_f32 v10, v10, v11
	s_nop 1
	v_mov_b32_dpp v64, v8 quad_perm:[1,0,3,2] row_mask:0xf bank_mask:0xf
	v_mov_b32_dpp v65, v10 quad_perm:[1,0,3,2] row_mask:0xf bank_mask:0xf
	v_perm_b32 v8, v8, v64, v67
	v_perm_b32 v10, v10, v65, v67
	v_cndmask_b32_e32 v73, v10, v8, vcc
	s_nop 1
	v_mov_b32_dpp v64, v73 quad_perm:[2,3,0,1] row_mask:0xf bank_mask:0xf
	v_cndmask_b32_e32 v9, v64, v10, vcc
	v_cndmask_b32_e32 v8, v8, v64, vcc
	global_store_dwordx2 v72, v[8:9], s[0:1]
	v_pk_mul_f32 v[56:57], v[56:57], v[34:35]
	v_pk_mul_f32 v[58:59], v[58:59], v[18:19]
	v_cvt_pk_bf16_f32 v56, v56, v57
	v_cvt_pk_bf16_f32 v58, v58, v59
	s_nop 1
	v_mov_b32_dpp v64, v56 quad_perm:[1,0,3,2] row_mask:0xf bank_mask:0xf
	v_mov_b32_dpp v65, v58 quad_perm:[1,0,3,2] row_mask:0xf bank_mask:0xf
	v_perm_b32 v56, v56, v64, v67
	v_perm_b32 v58, v58, v65, v67
	v_cndmask_b32_e32 v73, v58, v56, vcc
	s_nop 1
	v_mov_b32_dpp v64, v73 quad_perm:[2,3,0,1] row_mask:0xf bank_mask:0xf
	v_cndmask_b32_e32 v57, v64, v58, vcc
	v_cndmask_b32_e32 v56, v56, v64, vcc
	global_store_dwordx2 v72, v[56:57], s[0:1] offset:64
	v_pk_mul_f32 v[40:41], v[40:41], v[34:35]
	v_pk_mul_f32 v[42:43], v[42:43], v[18:19]
	v_cvt_pk_bf16_f32 v40, v40, v41
	v_cvt_pk_bf16_f32 v42, v42, v43
	s_nop 1
	v_mov_b32_dpp v64, v40 quad_perm:[1,0,3,2] row_mask:0xf bank_mask:0xf
	v_mov_b32_dpp v65, v42 quad_perm:[1,0,3,2] row_mask:0xf bank_mask:0xf
	v_perm_b32 v40, v40, v64, v67
	v_perm_b32 v42, v42, v65, v67
	v_cndmask_b32_e32 v73, v42, v40, vcc
	s_nop 1
	v_mov_b32_dpp v64, v73 quad_perm:[2,3,0,1] row_mask:0xf bank_mask:0xf
	v_cndmask_b32_e32 v41, v64, v42, vcc
	v_cndmask_b32_e32 v40, v40, v64, vcc
	global_store_dwordx2 v72, v[40:41], s[0:1] offset:128
	v_pk_mul_f32 v[24:25], v[24:25], v[34:35]
	v_pk_mul_f32 v[26:27], v[26:27], v[18:19]
	v_cvt_pk_bf16_f32 v24, v24, v25
	v_cvt_pk_bf16_f32 v26, v26, v27
	s_nop 1
	v_mov_b32_dpp v64, v24 quad_perm:[1,0,3,2] row_mask:0xf bank_mask:0xf
	v_mov_b32_dpp v65, v26 quad_perm:[1,0,3,2] row_mask:0xf bank_mask:0xf
	v_perm_b32 v24, v24, v64, v67
	v_perm_b32 v26, v26, v65, v67
	v_cndmask_b32_e32 v73, v26, v24, vcc
	s_nop 1
	v_mov_b32_dpp v64, v73 quad_perm:[2,3,0,1] row_mask:0xf bank_mask:0xf
	v_cndmask_b32_e32 v25, v64, v26, vcc
	v_cndmask_b32_e32 v24, v24, v64, vcc
	global_store_dwordx2 v72, v[24:25], s[0:1] offset:192
	v_add_u32_e32 v72, 0x4000, v72
	s_waitcnt lgkmcnt(0)
	v_rcp_f32_e32 v6, v6
	v_rcp_f32_e32 v7, v7
	v_rcp_f32_e32 v54, v54
	v_rcp_f32_e32 v55, v55
	s_nop 0
	v_pk_mul_f32 v[12:13], v[12:13], v[6:7]
	v_pk_mul_f32 v[14:15], v[14:15], v[54:55]
	v_cvt_pk_bf16_f32 v12, v12, v13
	v_cvt_pk_bf16_f32 v14, v14, v15
	s_nop 1
	v_mov_b32_dpp v64, v12 quad_perm:[1,0,3,2] row_mask:0xf bank_mask:0xf
	v_mov_b32_dpp v65, v14 quad_perm:[1,0,3,2] row_mask:0xf bank_mask:0xf
	v_perm_b32 v12, v12, v64, v67
	v_perm_b32 v14, v14, v65, v67
	v_cndmask_b32_e32 v73, v14, v12, vcc
	s_nop 1
	v_mov_b32_dpp v64, v73 quad_perm:[2,3,0,1] row_mask:0xf bank_mask:0xf
	v_cndmask_b32_e32 v13, v64, v14, vcc
	v_cndmask_b32_e32 v12, v12, v64, vcc
	global_store_dwordx2 v72, v[12:13], s[0:1]
	v_pk_mul_f32 v[60:61], v[60:61], v[6:7]
	v_pk_mul_f32 v[62:63], v[62:63], v[54:55]
	v_cvt_pk_bf16_f32 v60, v60, v61
	v_cvt_pk_bf16_f32 v62, v62, v63
	s_nop 1
	v_mov_b32_dpp v64, v60 quad_perm:[1,0,3,2] row_mask:0xf bank_mask:0xf
	v_mov_b32_dpp v65, v62 quad_perm:[1,0,3,2] row_mask:0xf bank_mask:0xf
	v_perm_b32 v60, v60, v64, v67
	v_perm_b32 v62, v62, v65, v67
	v_cndmask_b32_e32 v73, v62, v60, vcc
	s_nop 1
	v_mov_b32_dpp v64, v73 quad_perm:[2,3,0,1] row_mask:0xf bank_mask:0xf
	v_cndmask_b32_e32 v61, v64, v62, vcc
	v_cndmask_b32_e32 v60, v60, v64, vcc
	global_store_dwordx2 v72, v[60:61], s[0:1] offset:64
	v_pk_mul_f32 v[44:45], v[44:45], v[6:7]
	v_pk_mul_f32 v[46:47], v[46:47], v[54:55]
	v_cvt_pk_bf16_f32 v44, v44, v45
	v_cvt_pk_bf16_f32 v46, v46, v47
	s_nop 1
	v_mov_b32_dpp v64, v44 quad_perm:[1,0,3,2] row_mask:0xf bank_mask:0xf
	v_mov_b32_dpp v65, v46 quad_perm:[1,0,3,2] row_mask:0xf bank_mask:0xf
	v_perm_b32 v44, v44, v64, v67
	v_perm_b32 v46, v46, v65, v67
	v_cndmask_b32_e32 v73, v46, v44, vcc
	s_nop 1
	v_mov_b32_dpp v64, v73 quad_perm:[2,3,0,1] row_mask:0xf bank_mask:0xf
	v_cndmask_b32_e32 v45, v64, v46, vcc
	v_cndmask_b32_e32 v44, v44, v64, vcc
	global_store_dwordx2 v72, v[44:45], s[0:1] offset:128
	v_pk_mul_f32 v[28:29], v[28:29], v[6:7]
	v_pk_mul_f32 v[30:31], v[30:31], v[54:55]
	v_cvt_pk_bf16_f32 v28, v28, v29
	v_cvt_pk_bf16_f32 v30, v30, v31
	s_nop 1
	v_mov_b32_dpp v64, v28 quad_perm:[1,0,3,2] row_mask:0xf bank_mask:0xf
	v_mov_b32_dpp v65, v30 quad_perm:[1,0,3,2] row_mask:0xf bank_mask:0xf
	v_perm_b32 v28, v28, v64, v67
	v_perm_b32 v30, v30, v65, v67
	v_cndmask_b32_e32 v73, v30, v28, vcc
	s_nop 1
	v_mov_b32_dpp v64, v73 quad_perm:[2,3,0,1] row_mask:0xf bank_mask:0xf
	v_cndmask_b32_e32 v29, v64, v30, vcc
	v_cndmask_b32_e32 v28, v28, v64, vcc
	global_store_dwordx2 v72, v[28:29], s[0:1] offset:192
	s_add_i32 s2, s2, s94
	s_cmpk_gt_i32 s2, 0xff
	s_waitcnt vmcnt(63) expcnt(7) lgkmcnt(15)
	s_barrier
	s_cbranch_scc1 .LBB0_600
